# latent GEMM epilogue: the 8 per-row-group rstd loads issued together up front, per-block vmcnt(0) waits removed
# baseline (speedup 1.0000x reference)
; #define LAS __attribute__((address_space(3)))
; __device__ __forceinline__ unsigned pk4_fp8(float a, float b, float c, float d) { int p = __builtin_amdgcn_cvt_pk_fp8_f32(a, b, 0, false); p = __builtin_amdgcn_cvt_pk_fp8_f32(c, d, p, true); return (unsigned)p; }
; #define EPI_LOOP_ROWS  _Pragma("unroll") for (int ai = 0; ai < 2; ++ai) _Pragma("unroll") for (int m = 0; m < 4; ++m)
; __device__ __forceinline__ u32x4 pack8(f32x4 v0, f32x4 v1) { u32x4 w; w.x = cvt_pk_bf16(v0[0], v0[1]); w.y = cvt_pk_bf16(v0[2], v0[3]); w.z = cvt_pk_bf16(v1[0], v1[1]); w.w = cvt_pk_bf16(v1[2], v1[3]); return w; }
;     __device__ __forceinline__ void operator()(const Acc& acc, const Unit& u, int wr, int wc, int fr, int fq) const {
;     ...
;         EPI_LOOP_ROWS { const int row = u.pm * 256 + ai * HALF + wr * 64 + m * 16 + fr; const float s = rstd[row * 2 + which]; bf16_t* rowp = base + (size_t)row * ld + col0;
;             if (which == 0) {
; #pragma unroll
;                 for (int bj = 0; bj < 2; ++bj) *(u32x4*)(rowp + bj * HALF) = pack8(acc[ai][bj][m][0] * s, acc[ai][bj][m][1] * s);
;             } else {
;                 const f32x4 k0 = acc[ai][0][m][0] * s, k1 = acc[ai][0][m][1] * s;
;                 u32x2 w; w.x = pk4_fp8(k0[0], k0[1], k0[2], k0[3]); w.y = pk4_fp8(k1[0], k1[1], k1[2], k1[3]);
;                 *(u32x2*)((char*)kvb + (size_t)row * (LDKVB * 2) + (size_t)(u.pn - 5) * 512 + wc * 32 + 8 * fq) = w;
;                 const f32x4 v0 = acc[ai][1][m][0] * s, v1 = acc[ai][1][m][1] * s; const unsigned q0 = pk4_fp8(v0[0], v0[1], v0[2], v0[3]), q1 = pk4_fp8(v1[0], v1[1], v1[2], v1[3]);
;                 LAS unsigned char* sp = ldsx + 131072 + (wr * 4 + wc) * 2048 + (8 * fq) * 64 + 16 * m + fr;
;                 sp[0 * 64] = (unsigned char)(q0); sp[1 * 64] = (unsigned char)(q0 >> 8); sp[2 * 64] = (unsigned char)(q0 >> 16); sp[3 * 64] = (unsigned char)(q0 >> 24);
;                 sp[4 * 64] = (unsigned char)(q1); sp[5 * 64] = (unsigned char)(q1 >> 8); sp[6 * 64] = (unsigned char)(q1 >> 16); sp[7 * 64] = (unsigned char)(q1 >> 24);
.LBB0_362:
	s_add_u32 s8, s54, s8
	s_addc_u32 s9, s55, s9
	s_lshl_b32 s31, s57, 8
	v_add_u32_e32 v167, s31, v155
	v_lshl_or_b32 v152, v167, 1, s21
	v_ashrrev_i32_e32 v153, 31, v152
	v_lshl_add_u64 v[152:153], v[152:153], 2, s[68:69]
	global_load_dword v154, v[152:153], off
	v_or_b32_e32 v194, 16, v167
	v_lshl_or_b32 v192, v194, 1, s21
	v_ashrrev_i32_e32 v193, 31, v192
	v_lshl_add_u64 v[192:193], v[192:193], 2, s[68:69]
	global_load_dword v176, v[192:193], off
	v_or_b32_e32 v194, 32, v167
	v_lshl_or_b32 v192, v194, 1, s21
	v_ashrrev_i32_e32 v193, 31, v192
	v_lshl_add_u64 v[192:193], v[192:193], 2, s[68:69]
	global_load_dword v178, v[192:193], off
	v_or_b32_e32 v194, 48, v167
	v_lshl_or_b32 v192, v194, 1, s21
	v_ashrrev_i32_e32 v193, 31, v192
	v_lshl_add_u64 v[192:193], v[192:193], 2, s[68:69]
	global_load_dword v180, v[192:193], off
	v_add_u32_e32 v194, 0x80, v167
	v_lshl_or_b32 v192, v194, 1, s21
	v_ashrrev_i32_e32 v193, 31, v192
	v_lshl_add_u64 v[192:193], v[192:193], 2, s[68:69]
	global_load_dword v182, v[192:193], off
	v_add_u32_e32 v194, 0x90, v167
	v_lshl_or_b32 v192, v194, 1, s21
	v_ashrrev_i32_e32 v193, 31, v192
	v_lshl_add_u64 v[192:193], v[192:193], 2, s[68:69]
	global_load_dword v184, v[192:193], off
	v_add_u32_e32 v194, 0xa0, v167
	v_lshl_or_b32 v192, v194, 1, s21
	v_ashrrev_i32_e32 v193, 31, v192
	v_lshl_add_u64 v[192:193], v[192:193], 2, s[68:69]
	global_load_dword v186, v[192:193], off
	v_add_u32_e32 v194, 0xb0, v167
	v_lshl_or_b32 v192, v194, 1, s21
	v_ashrrev_i32_e32 v193, 31, v192
	v_lshl_add_u64 v[192:193], v[192:193], 2, s[68:69]
	global_load_dword v188, v[192:193], off
	s_add_i32 s10, s28, -5
	s_lshl_b64 s[28:29], s[10:11], 9
	s_mov_b64 s[36:37], -1
	s_and_b64 vcc, exec, s[34:35]
	s_cbranch_vccz .LBB0_364
	s_waitcnt vmcnt(0)
	v_pk_mul_f32 v[152:153], v[124:125], v[154:155] op_sel_hi:[1,0]
	v_mov_b32_e32 v170, 0
	v_pk_mul_f32 v[168:169], v[120:121], v[154:155] op_sel_hi:[1,0]
	v_cvt_pk_fp8_f32 v170, v152, v153
	v_mov_b32_e32 v171, 0
	v_cvt_pk_fp8_f32 v171, v168, v169
	v_pk_mul_f32 v[152:153], v[126:127], v[154:155] op_sel_hi:[1,0]
	v_pk_mul_f32 v[172:173], v[116:117], v[154:155] op_sel_hi:[1,0]
	v_mov_b32_e32 v174, 0
	v_pk_mul_f32 v[168:169], v[122:123], v[154:155] op_sel_hi:[1,0]
	v_cvt_pk_fp8_f32 v170, v152, v153 op_sel:[0,0,1]
	v_mov_b64_e32 v[152:153], s[74:75]
	v_cvt_pk_fp8_f32 v174, v172, v173
	v_cvt_pk_fp8_f32 v171, v168, v169 op_sel:[0,0,1]
	v_mad_i64_i32 v[152:153], s[36:37], v167, s38, v[152:153]
	v_pk_mul_f32 v[172:173], v[112:113], v[154:155] op_sel_hi:[1,0]
	v_mov_b32_e32 v175, 0
	v_lshl_add_u64 v[152:153], v[152:153], 0, s[28:29]
	v_cvt_pk_fp8_f32 v175, v172, v173
	v_lshl_add_u64 v[152:153], v[152:153], 0, s[14:15]
	v_pk_mul_f32 v[168:169], v[118:119], v[154:155] op_sel_hi:[1,0]
	v_lshl_add_u64 v[152:153], v[152:153], 0, v[136:137]
	v_cvt_pk_fp8_f32 v174, v168, v169 op_sel:[0,0,1]
	global_store_dwordx2 v[152:153], v[170:171], off
	v_pk_mul_f32 v[152:153], v[114:115], v[154:155] op_sel_hi:[1,0]
	s_mov_b64 s[36:37], 0
	v_cvt_pk_fp8_f32 v175, v152, v153 op_sel:[0,0,1]
	v_lshrrev_b32_e32 v152, 8, v174
	ds_write_b8 v161, v174
	ds_write_b8 v161, v152 offset:64
	ds_write_b8_d16_hi v161, v174 offset:128
	v_lshrrev_b32_e32 v152, 24, v174
	ds_write_b8 v161, v152 offset:192
	ds_write_b8 v161, v175 offset:256
	v_lshrrev_b32_e32 v152, 8, v175
	ds_write_b8 v161, v152 offset:320
	ds_write_b8_d16_hi v161, v175 offset:384
	v_lshrrev_b32_e32 v152, 24, v175
	ds_write_b8 v161, v152 offset:448

; #define LAS __attribute__((address_space(3)))
; __device__ __forceinline__ unsigned pk4_fp8(float a, float b, float c, float d) { int p = __builtin_amdgcn_cvt_pk_fp8_f32(a, b, 0, false); p = __builtin_amdgcn_cvt_pk_fp8_f32(c, d, p, true); return (unsigned)p; }
; #define EPI_LOOP_ROWS  _Pragma("unroll") for (int ai = 0; ai < 2; ++ai) _Pragma("unroll") for (int m = 0; m < 4; ++m)
; __device__ __forceinline__ u32x4 pack8(f32x4 v0, f32x4 v1) { u32x4 w; w.x = cvt_pk_bf16(v0[0], v0[1]); w.y = cvt_pk_bf16(v0[2], v0[3]); w.z = cvt_pk_bf16(v1[0], v1[1]); w.w = cvt_pk_bf16(v1[2], v1[3]); return w; }
;     __device__ __forceinline__ void operator()(const Acc& acc, const Unit& u, int wr, int wc, int fr, int fq) const {
;     ...
;         EPI_LOOP_ROWS { const int row = u.pm * 256 + ai * HALF + wr * 64 + m * 16 + fr; const float s = rstd[row * 2 + which]; bf16_t* rowp = base + (size_t)row * ld + col0;
;             if (which == 0) {
; #pragma unroll
;                 for (int bj = 0; bj < 2; ++bj) *(u32x4*)(rowp + bj * HALF) = pack8(acc[ai][bj][m][0] * s, acc[ai][bj][m][1] * s);
;             } else {
;                 const f32x4 k0 = acc[ai][0][m][0] * s, k1 = acc[ai][0][m][1] * s;
;                 u32x2 w; w.x = pk4_fp8(k0[0], k0[1], k0[2], k0[3]); w.y = pk4_fp8(k1[0], k1[1], k1[2], k1[3]);
;                 *(u32x2*)((char*)kvb + (size_t)row * (LDKVB * 2) + (size_t)(u.pn - 5) * 512 + wc * 32 + 8 * fq) = w;
;                 const f32x4 v0 = acc[ai][1][m][0] * s, v1 = acc[ai][1][m][1] * s; const unsigned q0 = pk4_fp8(v0[0], v0[1], v0[2], v0[3]), q1 = pk4_fp8(v1[0], v1[1], v1[2], v1[3]);
;                 LAS unsigned char* sp = ldsx + 131072 + (wr * 4 + wc) * 2048 + (8 * fq) * 64 + 16 * m + fr;
;                 sp[0 * 64] = (unsigned char)(q0); sp[1 * 64] = (unsigned char)(q0 >> 8); sp[2 * 64] = (unsigned char)(q0 >> 16); sp[3 * 64] = (unsigned char)(q0 >> 24);
;                 sp[4 * 64] = (unsigned char)(q1); sp[5 * 64] = (unsigned char)(q1 >> 8); sp[6 * 64] = (unsigned char)(q1 >> 16); sp[7 * 64] = (unsigned char)(q1 >> 24);
.LBB0_366:
	s_nop 1
	v_or_b32_e32 v113, 16, v167
	v_lshl_or_b32 v114, v113, 1, s21
	v_ashrrev_i32_e32 v115, 31, v114
	v_lshl_add_u64 v[114:115], v[114:115], 2, s[68:69]
	v_cndmask_b32_e64 v114, 0, 1, s[34:35]
	v_cmp_ne_u32_e64 s[8:9], 1, v114
	s_andn2_b64 vcc, exec, s[34:35]
	s_mov_b64 s[34:35], -1
	s_cbranch_vccnz .LBB0_368
	v_pk_mul_f32 v[114:115], v[108:109], v[176:177] op_sel_hi:[1,0]
	v_mov_b32_e32 v118, 0
	v_pk_mul_f32 v[116:117], v[104:105], v[176:177] op_sel_hi:[1,0]
	v_cvt_pk_fp8_f32 v118, v114, v115
	v_mov_b32_e32 v119, 0
	v_cvt_pk_fp8_f32 v119, v116, v117
	v_pk_mul_f32 v[114:115], v[110:111], v[176:177] op_sel_hi:[1,0]
	v_pk_mul_f32 v[120:121], v[100:101], v[176:177] op_sel_hi:[1,0]
	v_mov_b32_e32 v122, 0
	v_pk_mul_f32 v[116:117], v[106:107], v[176:177] op_sel_hi:[1,0]
	v_cvt_pk_fp8_f32 v118, v114, v115 op_sel:[0,0,1]
	v_mov_b64_e32 v[114:115], s[74:75]
	v_cvt_pk_fp8_f32 v122, v120, v121
	v_cvt_pk_fp8_f32 v119, v116, v117 op_sel:[0,0,1]
	v_mad_i64_i32 v[114:115], s[34:35], v113, s38, v[114:115]
	v_pk_mul_f32 v[120:121], v[96:97], v[176:177] op_sel_hi:[1,0]
	v_mov_b32_e32 v123, 0
	v_lshl_add_u64 v[114:115], v[114:115], 0, s[28:29]
	v_cvt_pk_fp8_f32 v123, v120, v121
	v_lshl_add_u64 v[114:115], v[114:115], 0, s[14:15]
	v_pk_mul_f32 v[116:117], v[102:103], v[176:177] op_sel_hi:[1,0]
	v_lshl_add_u64 v[114:115], v[114:115], 0, v[136:137]
	v_cvt_pk_fp8_f32 v122, v116, v117 op_sel:[0,0,1]
	global_store_dwordx2 v[114:115], v[118:119], off
	v_pk_mul_f32 v[114:115], v[98:99], v[176:177] op_sel_hi:[1,0]
	s_mov_b64 s[34:35], 0
	v_cvt_pk_fp8_f32 v123, v114, v115 op_sel:[0,0,1]
	v_lshrrev_b32_e32 v114, 8, v122
	ds_write_b8 v162, v122
	ds_write_b8 v162, v114 offset:64
	ds_write_b8_d16_hi v162, v122 offset:128
	v_lshrrev_b32_e32 v114, 24, v122
	ds_write_b8 v162, v114 offset:192
	ds_write_b8 v162, v123 offset:256
	v_lshrrev_b32_e32 v114, 8, v123
	ds_write_b8 v162, v114 offset:320
	ds_write_b8_d16_hi v162, v123 offset:384
	v_lshrrev_b32_e32 v114, 24, v123
	ds_write_b8 v162, v114 offset:448
.LBB0_368:
	s_andn2_b64 vcc, exec, s[34:35]
	s_cbranch_vccnz .LBB0_370
	v_mad_i64_i32 v[114:115], s[34:35], s30, v113, 0
	v_lshl_add_u64 v[114:115], v[114:115], 1, v[152:153]
	v_pk_mul_f32 v[110:111], v[110:111], v[176:177] op_sel_hi:[1,0]
	v_pk_mul_f32 v[108:109], v[108:109], v[176:177] op_sel_hi:[1,0]
	v_pk_mul_f32 v[116:117], v[106:107], v[176:177] op_sel_hi:[1,0]
	v_pk_mul_f32 v[106:107], v[104:105], v[176:177] op_sel_hi:[1,0]
	v_cvt_pk_bf16_f32 v104, v108, v109
	v_cvt_pk_bf16_f32 v105, v110, v111
	v_pk_mul_f32 v[102:103], v[102:103], v[176:177] op_sel_hi:[1,0]
	v_cvt_pk_bf16_f32 v106, v106, v107
	v_cvt_pk_bf16_f32 v107, v116, v117
	global_store_dwordx4 v[114:115], v[104:107], off
	v_pk_mul_f32 v[100:101], v[100:101], v[176:177] op_sel_hi:[1,0]
	s_nop 0
	v_pk_mul_f32 v[104:105], v[98:99], v[176:177] op_sel_hi:[1,0]
	v_pk_mul_f32 v[98:99], v[96:97], v[176:177] op_sel_hi:[1,0]
	v_cvt_pk_bf16_f32 v96, v100, v101
	v_cvt_pk_bf16_f32 v97, v102, v103
	s_nop 0
	v_cvt_pk_bf16_f32 v98, v98, v99
	v_cvt_pk_bf16_f32 v99, v104, v105
	global_store_dwordx4 v[114:115], v[96:99], off offset:256
.LBB0_370:
	s_nop 1
	v_or_b32_e32 v97, 32, v167
	v_lshl_or_b32 v98, v97, 1, s21
	v_ashrrev_i32_e32 v99, 31, v98
	v_lshl_add_u64 v[98:99], v[98:99], 2, s[68:69]
	s_and_b64 vcc, exec, s[8:9]
	s_mov_b64 s[34:35], -1
	s_cbranch_vccnz .LBB0_372
	v_pk_mul_f32 v[98:99], v[92:93], v[178:179] op_sel_hi:[1,0]
	v_mov_b32_e32 v102, 0
	v_pk_mul_f32 v[100:101], v[88:89], v[178:179] op_sel_hi:[1,0]
	v_cvt_pk_fp8_f32 v102, v98, v99
	v_mov_b32_e32 v103, 0
	v_cvt_pk_fp8_f32 v103, v100, v101
	v_pk_mul_f32 v[98:99], v[94:95], v[178:179] op_sel_hi:[1,0]
	v_pk_mul_f32 v[104:105], v[84:85], v[178:179] op_sel_hi:[1,0]
	v_mov_b32_e32 v106, 0
	v_pk_mul_f32 v[100:101], v[90:91], v[178:179] op_sel_hi:[1,0]
	v_cvt_pk_fp8_f32 v102, v98, v99 op_sel:[0,0,1]
	v_mov_b64_e32 v[98:99], s[74:75]
	v_cvt_pk_fp8_f32 v106, v104, v105
	v_cvt_pk_fp8_f32 v103, v100, v101 op_sel:[0,0,1]
	v_mad_i64_i32 v[98:99], s[34:35], v97, s38, v[98:99]
	v_pk_mul_f32 v[104:105], v[80:81], v[178:179] op_sel_hi:[1,0]
	v_mov_b32_e32 v107, 0
	v_lshl_add_u64 v[98:99], v[98:99], 0, s[28:29]
	v_cvt_pk_fp8_f32 v107, v104, v105
	v_lshl_add_u64 v[98:99], v[98:99], 0, s[14:15]
	v_pk_mul_f32 v[100:101], v[86:87], v[178:179] op_sel_hi:[1,0]
	v_lshl_add_u64 v[98:99], v[98:99], 0, v[136:137]
	v_cvt_pk_fp8_f32 v106, v100, v101 op_sel:[0,0,1]
	global_store_dwordx2 v[98:99], v[102:103], off
	v_pk_mul_f32 v[98:99], v[82:83], v[178:179] op_sel_hi:[1,0]
	s_mov_b64 s[34:35], 0
	v_cvt_pk_fp8_f32 v107, v98, v99 op_sel:[0,0,1]
	v_lshrrev_b32_e32 v98, 8, v106
	ds_write_b8 v163, v106
	ds_write_b8 v163, v98 offset:64
	ds_write_b8_d16_hi v163, v106 offset:128
	v_lshrrev_b32_e32 v98, 24, v106
	ds_write_b8 v163, v98 offset:192
	ds_write_b8 v163, v107 offset:256
	v_lshrrev_b32_e32 v98, 8, v107
	ds_write_b8 v163, v98 offset:320
	ds_write_b8_d16_hi v163, v107 offset:384
	v_lshrrev_b32_e32 v98, 24, v107
	ds_write_b8 v163, v98 offset:448
.LBB0_372:
	s_andn2_b64 vcc, exec, s[34:35]
	s_cbranch_vccnz .LBB0_374
	v_mad_i64_i32 v[98:99], s[34:35], s30, v97, 0
	v_lshl_add_u64 v[98:99], v[98:99], 1, v[152:153]
	v_pk_mul_f32 v[94:95], v[94:95], v[178:179] op_sel_hi:[1,0]
	v_pk_mul_f32 v[92:93], v[92:93], v[178:179] op_sel_hi:[1,0]
	v_pk_mul_f32 v[100:101], v[90:91], v[178:179] op_sel_hi:[1,0]
	v_pk_mul_f32 v[90:91], v[88:89], v[178:179] op_sel_hi:[1,0]
	v_cvt_pk_bf16_f32 v88, v92, v93
	v_cvt_pk_bf16_f32 v89, v94, v95
	v_pk_mul_f32 v[86:87], v[86:87], v[178:179] op_sel_hi:[1,0]
	v_cvt_pk_bf16_f32 v90, v90, v91
	v_cvt_pk_bf16_f32 v91, v100, v101
	global_store_dwordx4 v[98:99], v[88:91], off
	v_pk_mul_f32 v[84:85], v[84:85], v[178:179] op_sel_hi:[1,0]
	s_nop 0
	v_pk_mul_f32 v[88:89], v[82:83], v[178:179] op_sel_hi:[1,0]
	v_pk_mul_f32 v[82:83], v[80:81], v[178:179] op_sel_hi:[1,0]
	v_cvt_pk_bf16_f32 v80, v84, v85
	v_cvt_pk_bf16_f32 v81, v86, v87
	s_nop 0
	v_cvt_pk_bf16_f32 v82, v82, v83
	v_cvt_pk_bf16_f32 v83, v88, v89
	global_store_dwordx4 v[98:99], v[80:83], off offset:256
; #define LAS __attribute__((address_space(3)))
;     __device__ __forceinline__ void operator()(const Acc& acc, const Unit& u, int wr, int wc, int fr, int fq) const {
;     ...
;         EPI_LOOP_ROWS { const int row = u.pm * 256 + ai * HALF + wr * 64 + m * 16 + fr; const float s = rstd[row * 2 + which]; bf16_t* rowp = base + (size_t)row * ld + col0;
;             if (which == 0) {
; #pragma unroll
;                 for (int bj = 0; bj < 2; ++bj) *(u32x4*)(rowp + bj * HALF) = pack8(acc[ai][bj][m][0] * s, acc[ai][bj][m][1] * s);
;             } else {
;                 const f32x4 k0 = acc[ai][0][m][0] * s, k1 = acc[ai][0][m][1] * s;
;                 u32x2 w; w.x = pk4_fp8(k0[0], k0[1], k0[2], k0[3]); w.y = pk4_fp8(k1[0], k1[1], k1[2], k1[3]);
;                 *(u32x2*)((char*)kvb + (size_t)row * (LDKVB * 2) + (size_t)(u.pn - 5) * 512 + wc * 32 + 8 * fq) = w;
;                 const f32x4 v0 = acc[ai][1][m][0] * s, v1 = acc[ai][1][m][1] * s; const unsigned q0 = pk4_fp8(v0[0], v0[1], v0[2], v0[3]), q1 = pk4_fp8(v1[0], v1[1], v1[2], v1[3]);
;                 LAS unsigned char* sp = ldsx + 131072 + (wr * 4 + wc) * 2048 + (8 * fq) * 64 + 16 * m + fr;
;                 sp[0 * 64] = (unsigned char)(q0); sp[1 * 64] = (unsigned char)(q0 >> 8); sp[2 * 64] = (unsigned char)(q0 >> 16); sp[3 * 64] = (unsigned char)(q0 >> 24);
;                 sp[4 * 64] = (unsigned char)(q1); sp[5 * 64] = (unsigned char)(q1 >> 8); sp[6 * 64] = (unsigned char)(q1 >> 16); sp[7 * 64] = (unsigned char)(q1 >> 24);
;                 if (m == 3) {
;                     asm volatile("s_waitcnt lgkmcnt(0)" ::: "memory");
;                     const int pm = u.pm, sq = pm < 64 ? 0 : (pm < 128 ? 1 : 2), slen = sq < 2 ? SEQ_P : SEQ_S, pos0 = pm * 256 - (sq < 2 ? sq * SEQ_P : T_PROMPT);
;                     unsigned char* vth = vt + (size_t)sq * (6 * 128 * SEQ_P) + (size_t)(u.pn - 5) * 128 * slen;
;                     const int lane_ = fq * 16 + fr; LAS unsigned char* wb = ldsx + 131072 + (wr * 4 + wc) * 2048;
; #pragma unroll
;                     for (int c2 = 0; c2 < 2; ++c2) { const int id = lane_ + 64 * c2, col = id >> 2, seg = id & 3;
;                         const u32x4 vv = *(const LAS u32x4*)(wb + col * 64 + seg * 16);
;                         *(u32x4*)(vth + (size_t)(32 * wc + col) * slen + pos0 + ai * HALF + wr * 64 + seg * 16) = vv; }
.LBB0_374:
	v_or_b32_e32 v85, 48, v167
	s_nop 0
	v_lshl_or_b32 v80, v85, 1, s21
	v_ashrrev_i32_e32 v81, 31, v80
	v_lshl_add_u64 v[80:81], v[80:81], 2, s[68:69]
	s_cmpk_lt_i32 s57, 0x80
	s_cselect_b32 s34, 1, 2
	s_cmp_gt_i32 s57, 63
	s_cselect_b32 s34, s34, 0
	s_lshl_b32 s35, s34, 14
	s_cmpk_lt_i32 s57, 0x80
	s_cselect_b32 s35, s35, 0x8000
	s_cselect_b32 s58, 14, 13
	s_sub_i32 s31, s31, s35
	s_mul_i32 s57, s34, 0xc00000
	s_lshl_b64 s[34:35], s[10:11], 7
	s_lshl_b64 s[34:35], s[34:35], s58
	s_lshl_b32 s10, s31, 7
	s_mov_b64 s[36:37], -1
	s_and_b64 vcc, exec, s[8:9]
	v_lshlrev_b64 v[82:83], 7, v[140:141]
	v_lshlrev_b64 v[80:81], 7, v[142:143]
	s_cbranch_vccnz .LBB0_376
	v_pk_mul_f32 v[86:87], v[76:77], v[180:181] op_sel_hi:[1,0]
	v_mov_b32_e32 v90, 0
	v_pk_mul_f32 v[88:89], v[72:73], v[180:181] op_sel_hi:[1,0]
	v_cvt_pk_fp8_f32 v90, v86, v87
	v_mov_b32_e32 v91, 0
	v_cvt_pk_fp8_f32 v91, v88, v89
	v_pk_mul_f32 v[86:87], v[78:79], v[180:181] op_sel_hi:[1,0]
	v_pk_mul_f32 v[92:93], v[68:69], v[180:181] op_sel_hi:[1,0]
	v_mov_b32_e32 v94, 0
	v_pk_mul_f32 v[88:89], v[74:75], v[180:181] op_sel_hi:[1,0]
	v_cvt_pk_fp8_f32 v90, v86, v87 op_sel:[0,0,1]
	v_mov_b64_e32 v[86:87], s[74:75]
	v_cvt_pk_fp8_f32 v94, v92, v93
	v_cvt_pk_fp8_f32 v91, v88, v89 op_sel:[0,0,1]
	v_mad_i64_i32 v[86:87], s[36:37], v85, s38, v[86:87]
	v_pk_mul_f32 v[92:93], v[64:65], v[180:181] op_sel_hi:[1,0]
	v_mov_b32_e32 v95, 0
	v_lshl_add_u64 v[86:87], v[86:87], 0, s[28:29]
	v_cvt_pk_fp8_f32 v95, v92, v93
	v_lshl_add_u64 v[86:87], v[86:87], 0, s[14:15]
	v_pk_mul_f32 v[88:89], v[70:71], v[180:181] op_sel_hi:[1,0]
	v_lshl_add_u64 v[86:87], v[86:87], 0, v[136:137]
	v_cvt_pk_fp8_f32 v94, v88, v89 op_sel:[0,0,1]
	global_store_dwordx2 v[86:87], v[90:91], off
	v_pk_mul_f32 v[86:87], v[66:67], v[180:181] op_sel_hi:[1,0]
	s_add_u32 s36, s76, s57
	v_cvt_pk_fp8_f32 v95, v86, v87 op_sel:[0,0,1]
	v_lshrrev_b32_e32 v86, 8, v94
	ds_write_b8 v164, v94
	ds_write_b8 v164, v86 offset:64
	ds_write_b8_d16_hi v164, v94 offset:128
	v_lshrrev_b32_e32 v86, 24, v94
	ds_write_b8 v164, v86 offset:192
	ds_write_b8 v164, v95 offset:256
	v_lshrrev_b32_e32 v86, 8, v95
	s_addc_u32 s37, s77, 0
	ds_write_b8 v164, v86 offset:320
	ds_write_b8_d16_hi v164, v95 offset:384
	v_lshrrev_b32_e32 v86, 24, v95
	s_add_u32 s36, s36, s34
	ds_write_b8 v164, v86 offset:448
	s_addc_u32 s37, s37, s35
	s_waitcnt lgkmcnt(0)
	s_add_u32 s36, s36, s10
	s_addc_u32 s37, s37, 0
	ds_read_b128 v[86:89], v165
	ds_read_b128 v[90:93], v166
	s_add_u32 s36, s36, s44
	s_addc_u32 s37, s37, s48
	v_lshl_add_u64 v[94:95], s[36:37], 0, v[138:139]
	v_lshl_add_u64 v[96:97], v[94:95], 0, v[82:83]
	s_waitcnt lgkmcnt(1)
	global_store_dwordx4 v[96:97], v[86:89], off
	s_mov_b64 s[36:37], 0
	s_nop 0
	v_lshl_add_u64 v[86:87], v[94:95], 0, v[80:81]
	s_waitcnt lgkmcnt(0)
	global_store_dwordx4 v[86:87], v[90:93], off
	s_waitcnt lgkmcnt(0)
.LBB0_376:
	s_andn2_b64 vcc, exec, s[36:37]
	s_cbranch_vccnz .LBB0_378
	v_mad_i64_i32 v[86:87], s[36:37], s30, v85, 0
	v_lshl_add_u64 v[86:87], v[86:87], 1, v[152:153]
	v_pk_mul_f32 v[78:79], v[78:79], v[180:181] op_sel_hi:[1,0]
	v_pk_mul_f32 v[76:77], v[76:77], v[180:181] op_sel_hi:[1,0]
	v_pk_mul_f32 v[88:89], v[74:75], v[180:181] op_sel_hi:[1,0]
	v_pk_mul_f32 v[74:75], v[72:73], v[180:181] op_sel_hi:[1,0]
	v_cvt_pk_bf16_f32 v72, v76, v77
	v_cvt_pk_bf16_f32 v73, v78, v79
	v_pk_mul_f32 v[70:71], v[70:71], v[180:181] op_sel_hi:[1,0]
	v_cvt_pk_bf16_f32 v74, v74, v75
	v_cvt_pk_bf16_f32 v75, v88, v89
	global_store_dwordx4 v[86:87], v[72:75], off
	v_pk_mul_f32 v[68:69], v[68:69], v[180:181] op_sel_hi:[1,0]
	s_nop 0
	v_pk_mul_f32 v[72:73], v[66:67], v[180:181] op_sel_hi:[1,0]
	v_pk_mul_f32 v[66:67], v[64:65], v[180:181] op_sel_hi:[1,0]
	v_cvt_pk_bf16_f32 v64, v68, v69
	v_cvt_pk_bf16_f32 v65, v70, v71
	s_nop 0
	v_cvt_pk_bf16_f32 v66, v66, v67
	v_cvt_pk_bf16_f32 v67, v72, v73
	global_store_dwordx4 v[86:87], v[64:67], off offset:256
.LBB0_378:
	s_nop 1
	v_add_u32_e32 v65, 0x80, v167
	v_lshl_or_b32 v66, v65, 1, s21
	v_ashrrev_i32_e32 v67, 31, v66
	v_lshl_add_u64 v[66:67], v[66:67], 2, s[68:69]
	s_and_b64 vcc, exec, s[8:9]
	s_mov_b64 s[36:37], -1
	s_cbranch_vccnz .LBB0_380
	v_pk_mul_f32 v[66:67], v[60:61], v[182:183] op_sel_hi:[1,0]
	v_mov_b32_e32 v70, 0
	v_pk_mul_f32 v[68:69], v[56:57], v[182:183] op_sel_hi:[1,0]
	v_cvt_pk_fp8_f32 v70, v66, v67
	v_mov_b32_e32 v71, 0
	v_cvt_pk_fp8_f32 v71, v68, v69
	v_pk_mul_f32 v[66:67], v[62:63], v[182:183] op_sel_hi:[1,0]
	v_pk_mul_f32 v[72:73], v[52:53], v[182:183] op_sel_hi:[1,0]
	v_mov_b32_e32 v74, 0
	v_pk_mul_f32 v[68:69], v[58:59], v[182:183] op_sel_hi:[1,0]
	v_cvt_pk_fp8_f32 v70, v66, v67 op_sel:[0,0,1]
	v_mov_b64_e32 v[66:67], s[74:75]
	v_cvt_pk_fp8_f32 v74, v72, v73
	v_cvt_pk_fp8_f32 v71, v68, v69 op_sel:[0,0,1]
	v_mad_i64_i32 v[66:67], s[36:37], v65, s38, v[66:67]
	v_pk_mul_f32 v[72:73], v[48:49], v[182:183] op_sel_hi:[1,0]
	v_mov_b32_e32 v75, 0
	v_lshl_add_u64 v[66:67], v[66:67], 0, s[28:29]
	v_cvt_pk_fp8_f32 v75, v72, v73
	v_lshl_add_u64 v[66:67], v[66:67], 0, s[14:15]
	v_pk_mul_f32 v[68:69], v[54:55], v[182:183] op_sel_hi:[1,0]
	v_lshl_add_u64 v[66:67], v[66:67], 0, v[136:137]
	v_cvt_pk_fp8_f32 v74, v68, v69 op_sel:[0,0,1]
	global_store_dwordx2 v[66:67], v[70:71], off
	v_pk_mul_f32 v[66:67], v[50:51], v[182:183] op_sel_hi:[1,0]
	s_mov_b64 s[36:37], 0
	v_cvt_pk_fp8_f32 v75, v66, v67 op_sel:[0,0,1]
	v_lshrrev_b32_e32 v66, 8, v74
	ds_write_b8 v161, v74
	ds_write_b8 v161, v66 offset:64
	ds_write_b8_d16_hi v161, v74 offset:128
	v_lshrrev_b32_e32 v66, 24, v74
	ds_write_b8 v161, v66 offset:192
	ds_write_b8 v161, v75 offset:256
	v_lshrrev_b32_e32 v66, 8, v75
	ds_write_b8 v161, v66 offset:320
	ds_write_b8_d16_hi v161, v75 offset:384
	v_lshrrev_b32_e32 v66, 24, v75
	ds_write_b8 v161, v66 offset:448
; #define LAS __attribute__((address_space(3)))
; __device__ __forceinline__ unsigned pk4_fp8(float a, float b, float c, float d) { int p = __builtin_amdgcn_cvt_pk_fp8_f32(a, b, 0, false); p = __builtin_amdgcn_cvt_pk_fp8_f32(c, d, p, true); return (unsigned)p; }
; #define EPI_LOOP_ROWS  _Pragma("unroll") for (int ai = 0; ai < 2; ++ai) _Pragma("unroll") for (int m = 0; m < 4; ++m)
; __device__ __forceinline__ u32x4 pack8(f32x4 v0, f32x4 v1) { u32x4 w; w.x = cvt_pk_bf16(v0[0], v0[1]); w.y = cvt_pk_bf16(v0[2], v0[3]); w.z = cvt_pk_bf16(v1[0], v1[1]); w.w = cvt_pk_bf16(v1[2], v1[3]); return w; }
;     __device__ __forceinline__ void operator()(const Acc& acc, const Unit& u, int wr, int wc, int fr, int fq) const {
;     ...
;         EPI_LOOP_ROWS { const int row = u.pm * 256 + ai * HALF + wr * 64 + m * 16 + fr; const float s = rstd[row * 2 + which]; bf16_t* rowp = base + (size_t)row * ld + col0;
;             if (which == 0) {
; #pragma unroll
;                 for (int bj = 0; bj < 2; ++bj) *(u32x4*)(rowp + bj * HALF) = pack8(acc[ai][bj][m][0] * s, acc[ai][bj][m][1] * s);
;             } else {
;                 const f32x4 k0 = acc[ai][0][m][0] * s, k1 = acc[ai][0][m][1] * s;
;                 u32x2 w; w.x = pk4_fp8(k0[0], k0[1], k0[2], k0[3]); w.y = pk4_fp8(k1[0], k1[1], k1[2], k1[3]);
;                 *(u32x2*)((char*)kvb + (size_t)row * (LDKVB * 2) + (size_t)(u.pn - 5) * 512 + wc * 32 + 8 * fq) = w;
;                 const f32x4 v0 = acc[ai][1][m][0] * s, v1 = acc[ai][1][m][1] * s; const unsigned q0 = pk4_fp8(v0[0], v0[1], v0[2], v0[3]), q1 = pk4_fp8(v1[0], v1[1], v1[2], v1[3]);
;                 LAS unsigned char* sp = ldsx + 131072 + (wr * 4 + wc) * 2048 + (8 * fq) * 64 + 16 * m + fr;
;                 sp[0 * 64] = (unsigned char)(q0); sp[1 * 64] = (unsigned char)(q0 >> 8); sp[2 * 64] = (unsigned char)(q0 >> 16); sp[3 * 64] = (unsigned char)(q0 >> 24);
;                 sp[4 * 64] = (unsigned char)(q1); sp[5 * 64] = (unsigned char)(q1 >> 8); sp[6 * 64] = (unsigned char)(q1 >> 16); sp[7 * 64] = (unsigned char)(q1 >> 24);
.LBB0_380:
	s_andn2_b64 vcc, exec, s[36:37]
	s_cbranch_vccnz .LBB0_382
	v_mad_i64_i32 v[66:67], s[36:37], s30, v65, 0
	v_lshl_add_u64 v[66:67], v[66:67], 1, v[152:153]
	v_pk_mul_f32 v[62:63], v[62:63], v[182:183] op_sel_hi:[1,0]
	v_pk_mul_f32 v[60:61], v[60:61], v[182:183] op_sel_hi:[1,0]
	v_pk_mul_f32 v[68:69], v[58:59], v[182:183] op_sel_hi:[1,0]
	v_pk_mul_f32 v[58:59], v[56:57], v[182:183] op_sel_hi:[1,0]
	v_cvt_pk_bf16_f32 v56, v60, v61
	v_cvt_pk_bf16_f32 v57, v62, v63
	v_pk_mul_f32 v[54:55], v[54:55], v[182:183] op_sel_hi:[1,0]
	v_cvt_pk_bf16_f32 v58, v58, v59
	v_cvt_pk_bf16_f32 v59, v68, v69
	global_store_dwordx4 v[66:67], v[56:59], off
	v_pk_mul_f32 v[52:53], v[52:53], v[182:183] op_sel_hi:[1,0]
	s_nop 0
	v_pk_mul_f32 v[56:57], v[50:51], v[182:183] op_sel_hi:[1,0]
	v_pk_mul_f32 v[50:51], v[48:49], v[182:183] op_sel_hi:[1,0]
	v_cvt_pk_bf16_f32 v48, v52, v53
	v_cvt_pk_bf16_f32 v49, v54, v55
	s_nop 0
	v_cvt_pk_bf16_f32 v50, v50, v51
	v_cvt_pk_bf16_f32 v51, v56, v57
	global_store_dwordx4 v[66:67], v[48:51], off offset:256
.LBB0_382:
	s_nop 1
	v_add_u32_e32 v49, 0x90, v167
	v_lshl_or_b32 v50, v49, 1, s21
	v_ashrrev_i32_e32 v51, 31, v50
	v_lshl_add_u64 v[50:51], v[50:51], 2, s[68:69]
	s_and_b64 vcc, exec, s[8:9]
	s_mov_b64 s[36:37], -1
	s_cbranch_vccnz .LBB0_384
	v_pk_mul_f32 v[50:51], v[44:45], v[184:185] op_sel_hi:[1,0]
	v_mov_b32_e32 v54, 0
	v_pk_mul_f32 v[52:53], v[40:41], v[184:185] op_sel_hi:[1,0]
	v_cvt_pk_fp8_f32 v54, v50, v51
	v_mov_b32_e32 v55, 0
	v_cvt_pk_fp8_f32 v55, v52, v53
	v_pk_mul_f32 v[50:51], v[46:47], v[184:185] op_sel_hi:[1,0]
	v_pk_mul_f32 v[56:57], v[36:37], v[184:185] op_sel_hi:[1,0]
	v_mov_b32_e32 v58, 0
	v_pk_mul_f32 v[52:53], v[42:43], v[184:185] op_sel_hi:[1,0]
	v_cvt_pk_fp8_f32 v54, v50, v51 op_sel:[0,0,1]
	v_mov_b64_e32 v[50:51], s[74:75]
	v_cvt_pk_fp8_f32 v58, v56, v57
	v_cvt_pk_fp8_f32 v55, v52, v53 op_sel:[0,0,1]
	v_mad_i64_i32 v[50:51], s[36:37], v49, s38, v[50:51]
	v_pk_mul_f32 v[56:57], v[32:33], v[184:185] op_sel_hi:[1,0]
	v_mov_b32_e32 v59, 0
	v_lshl_add_u64 v[50:51], v[50:51], 0, s[28:29]
	v_cvt_pk_fp8_f32 v59, v56, v57
	v_lshl_add_u64 v[50:51], v[50:51], 0, s[14:15]
	v_pk_mul_f32 v[52:53], v[38:39], v[184:185] op_sel_hi:[1,0]
	v_lshl_add_u64 v[50:51], v[50:51], 0, v[136:137]
	v_cvt_pk_fp8_f32 v58, v52, v53 op_sel:[0,0,1]
	global_store_dwordx2 v[50:51], v[54:55], off
	v_pk_mul_f32 v[50:51], v[34:35], v[184:185] op_sel_hi:[1,0]
	s_mov_b64 s[36:37], 0
	v_cvt_pk_fp8_f32 v59, v50, v51 op_sel:[0,0,1]
	v_lshrrev_b32_e32 v50, 8, v58
	ds_write_b8 v162, v58
	ds_write_b8 v162, v50 offset:64
	ds_write_b8_d16_hi v162, v58 offset:128
	v_lshrrev_b32_e32 v50, 24, v58
	ds_write_b8 v162, v50 offset:192
	ds_write_b8 v162, v59 offset:256
	v_lshrrev_b32_e32 v50, 8, v59
	ds_write_b8 v162, v50 offset:320
	ds_write_b8_d16_hi v162, v59 offset:384
	v_lshrrev_b32_e32 v50, 24, v59
	ds_write_b8 v162, v50 offset:448
.LBB0_384:
	s_andn2_b64 vcc, exec, s[36:37]
	s_cbranch_vccnz .LBB0_386
	v_mad_i64_i32 v[50:51], s[36:37], s30, v49, 0
	v_lshl_add_u64 v[50:51], v[50:51], 1, v[152:153]
	v_pk_mul_f32 v[46:47], v[46:47], v[184:185] op_sel_hi:[1,0]
	v_pk_mul_f32 v[44:45], v[44:45], v[184:185] op_sel_hi:[1,0]
	v_pk_mul_f32 v[52:53], v[42:43], v[184:185] op_sel_hi:[1,0]
	v_pk_mul_f32 v[42:43], v[40:41], v[184:185] op_sel_hi:[1,0]
	v_cvt_pk_bf16_f32 v40, v44, v45
	v_cvt_pk_bf16_f32 v41, v46, v47
	v_pk_mul_f32 v[38:39], v[38:39], v[184:185] op_sel_hi:[1,0]
	v_cvt_pk_bf16_f32 v42, v42, v43
	v_cvt_pk_bf16_f32 v43, v52, v53
	global_store_dwordx4 v[50:51], v[40:43], off
	v_pk_mul_f32 v[36:37], v[36:37], v[184:185] op_sel_hi:[1,0]
	s_nop 0
	v_pk_mul_f32 v[40:41], v[34:35], v[184:185] op_sel_hi:[1,0]
	v_pk_mul_f32 v[34:35], v[32:33], v[184:185] op_sel_hi:[1,0]
	v_cvt_pk_bf16_f32 v32, v36, v37
	v_cvt_pk_bf16_f32 v33, v38, v39
	s_nop 0
	v_cvt_pk_bf16_f32 v34, v34, v35
	v_cvt_pk_bf16_f32 v35, v40, v41
	global_store_dwordx4 v[50:51], v[32:35], off offset:256
;     __device__ __forceinline__ void operator()(const Acc& acc, const Unit& u, int wr, int wc, int fr, int fq) const {
;     ...
;         EPI_LOOP_ROWS { const int row = u.pm * 256 + ai * HALF + wr * 64 + m * 16 + fr; const float s = rstd[row * 2 + which]; bf16_t* rowp = base + (size_t)row * ld + col0;
;             if (which == 0) {
; #pragma unroll
;                 for (int bj = 0; bj < 2; ++bj) *(u32x4*)(rowp + bj * HALF) = pack8(acc[ai][bj][m][0] * s, acc[ai][bj][m][1] * s);
;             } else {
;                 const f32x4 k0 = acc[ai][0][m][0] * s, k1 = acc[ai][0][m][1] * s;
;                 u32x2 w; w.x = pk4_fp8(k0[0], k0[1], k0[2], k0[3]); w.y = pk4_fp8(k1[0], k1[1], k1[2], k1[3]);
;                 *(u32x2*)((char*)kvb + (size_t)row * (LDKVB * 2) + (size_t)(u.pn - 5) * 512 + wc * 32 + 8 * fq) = w;
;                 const f32x4 v0 = acc[ai][1][m][0] * s, v1 = acc[ai][1][m][1] * s; const unsigned q0 = pk4_fp8(v0[0], v0[1], v0[2], v0[3]), q1 = pk4_fp8(v1[0], v1[1], v1[2], v1[3]);
;                 LAS unsigned char* sp = ldsx + 131072 + (wr * 4 + wc) * 2048 + (8 * fq) * 64 + 16 * m + fr;
;                 sp[0 * 64] = (unsigned char)(q0); sp[1 * 64] = (unsigned char)(q0 >> 8); sp[2 * 64] = (unsigned char)(q0 >> 16); sp[3 * 64] = (unsigned char)(q0 >> 24);
;                 sp[4 * 64] = (unsigned char)(q1); sp[5 * 64] = (unsigned char)(q1 >> 8); sp[6 * 64] = (unsigned char)(q1 >> 16); sp[7 * 64] = (unsigned char)(q1 >> 24);
;                 if (m == 3) {
;                     asm volatile("s_waitcnt lgkmcnt(0)" ::: "memory");
;                     const int pm = u.pm, sq = pm < 64 ? 0 : (pm < 128 ? 1 : 2), slen = sq < 2 ? SEQ_P : SEQ_S, pos0 = pm * 256 - (sq < 2 ? sq * SEQ_P : T_PROMPT);
;                     unsigned char* vth = vt + (size_t)sq * (6 * 128 * SEQ_P) + (size_t)(u.pn - 5) * 128 * slen;
;                     const int lane_ = fq * 16 + fr; LAS unsigned char* wb = ldsx + 131072 + (wr * 4 + wc) * 2048;
; #pragma unroll
;                     for (int c2 = 0; c2 < 2; ++c2) { const int id = lane_ + 64 * c2, col = id >> 2, seg = id & 3;
;                         const u32x4 vv = *(const LAS u32x4*)(wb + col * 64 + seg * 16);
;                         *(u32x4*)(vth + (size_t)(32 * wc + col) * slen + pos0 + ai * HALF + wr * 64 + seg * 16) = vv; }
;                     asm volatile("s_waitcnt lgkmcnt(0)" ::: "memory");
;                 }
.LBB0_386:
	s_nop 1
	v_add_u32_e32 v33, 0xa0, v167
	v_lshl_or_b32 v34, v33, 1, s21
	v_ashrrev_i32_e32 v35, 31, v34
	v_lshl_add_u64 v[34:35], v[34:35], 2, s[68:69]
	s_and_b64 vcc, exec, s[8:9]
	s_mov_b64 s[36:37], -1
	s_cbranch_vccnz .LBB0_388
	v_pk_mul_f32 v[34:35], v[28:29], v[186:187] op_sel_hi:[1,0]
	v_mov_b32_e32 v38, 0
	v_pk_mul_f32 v[36:37], v[24:25], v[186:187] op_sel_hi:[1,0]
	v_cvt_pk_fp8_f32 v38, v34, v35
	v_mov_b32_e32 v39, 0
	v_cvt_pk_fp8_f32 v39, v36, v37
	v_pk_mul_f32 v[34:35], v[30:31], v[186:187] op_sel_hi:[1,0]
	v_pk_mul_f32 v[40:41], v[20:21], v[186:187] op_sel_hi:[1,0]
	v_mov_b32_e32 v42, 0
	v_pk_mul_f32 v[36:37], v[26:27], v[186:187] op_sel_hi:[1,0]
	v_cvt_pk_fp8_f32 v38, v34, v35 op_sel:[0,0,1]
	v_mov_b64_e32 v[34:35], s[74:75]
	v_cvt_pk_fp8_f32 v42, v40, v41
	v_cvt_pk_fp8_f32 v39, v36, v37 op_sel:[0,0,1]
	v_mad_i64_i32 v[34:35], s[36:37], v33, s38, v[34:35]
	v_pk_mul_f32 v[40:41], v[16:17], v[186:187] op_sel_hi:[1,0]
	v_mov_b32_e32 v43, 0
	v_lshl_add_u64 v[34:35], v[34:35], 0, s[28:29]
	v_cvt_pk_fp8_f32 v43, v40, v41
	v_lshl_add_u64 v[34:35], v[34:35], 0, s[14:15]
	v_pk_mul_f32 v[36:37], v[22:23], v[186:187] op_sel_hi:[1,0]
	v_lshl_add_u64 v[34:35], v[34:35], 0, v[136:137]
	v_cvt_pk_fp8_f32 v42, v36, v37 op_sel:[0,0,1]
	global_store_dwordx2 v[34:35], v[38:39], off
	v_pk_mul_f32 v[34:35], v[18:19], v[186:187] op_sel_hi:[1,0]
	s_mov_b64 s[36:37], 0
	v_cvt_pk_fp8_f32 v43, v34, v35 op_sel:[0,0,1]
	v_lshrrev_b32_e32 v34, 8, v42
	ds_write_b8 v163, v42
	ds_write_b8 v163, v34 offset:64
	ds_write_b8_d16_hi v163, v42 offset:128
	v_lshrrev_b32_e32 v34, 24, v42
	ds_write_b8 v163, v34 offset:192
	ds_write_b8 v163, v43 offset:256
	v_lshrrev_b32_e32 v34, 8, v43
	ds_write_b8 v163, v34 offset:320
	ds_write_b8_d16_hi v163, v43 offset:384
	v_lshrrev_b32_e32 v34, 24, v43
	ds_write_b8 v163, v34 offset:448
.LBB0_388:
	s_andn2_b64 vcc, exec, s[36:37]
	s_cbranch_vccnz .LBB0_390
	v_mad_i64_i32 v[34:35], s[36:37], s30, v33, 0
	v_lshl_add_u64 v[34:35], v[34:35], 1, v[152:153]
	v_pk_mul_f32 v[30:31], v[30:31], v[186:187] op_sel_hi:[1,0]
	v_pk_mul_f32 v[28:29], v[28:29], v[186:187] op_sel_hi:[1,0]
	v_pk_mul_f32 v[36:37], v[26:27], v[186:187] op_sel_hi:[1,0]
	v_pk_mul_f32 v[26:27], v[24:25], v[186:187] op_sel_hi:[1,0]
	v_cvt_pk_bf16_f32 v24, v28, v29
	v_cvt_pk_bf16_f32 v25, v30, v31
	v_pk_mul_f32 v[22:23], v[22:23], v[186:187] op_sel_hi:[1,0]
	v_cvt_pk_bf16_f32 v26, v26, v27
	v_cvt_pk_bf16_f32 v27, v36, v37
	global_store_dwordx4 v[34:35], v[24:27], off
	v_pk_mul_f32 v[20:21], v[20:21], v[186:187] op_sel_hi:[1,0]
	s_nop 0
	v_pk_mul_f32 v[24:25], v[18:19], v[186:187] op_sel_hi:[1,0]
	v_pk_mul_f32 v[18:19], v[16:17], v[186:187] op_sel_hi:[1,0]
	v_cvt_pk_bf16_f32 v16, v20, v21
	v_cvt_pk_bf16_f32 v17, v22, v23
	s_nop 0
	v_cvt_pk_bf16_f32 v18, v18, v19
	v_cvt_pk_bf16_f32 v19, v24, v25
	global_store_dwordx4 v[34:35], v[16:19], off offset:256
.LBB0_390:
	s_nop 1
	v_add_u32_e32 v17, 0xb0, v167
	v_lshl_or_b32 v18, v17, 1, s21
	v_ashrrev_i32_e32 v19, 31, v18
	v_lshl_add_u64 v[18:19], v[18:19], 2, s[68:69]
	s_and_b64 vcc, exec, s[8:9]
	s_mov_b64 s[8:9], -1
	s_cbranch_vccnz .LBB0_393
	v_pk_mul_f32 v[18:19], v[12:13], v[188:189] op_sel_hi:[1,0]
	v_mov_b32_e32 v22, 0
	v_pk_mul_f32 v[20:21], v[8:9], v[188:189] op_sel_hi:[1,0]
	v_cvt_pk_fp8_f32 v22, v18, v19
	v_mov_b32_e32 v23, 0
	v_cvt_pk_fp8_f32 v23, v20, v21
	v_pk_mul_f32 v[18:19], v[14:15], v[188:189] op_sel_hi:[1,0]
	v_pk_mul_f32 v[24:25], v[4:5], v[188:189] op_sel_hi:[1,0]
	v_mov_b32_e32 v26, 0
	v_pk_mul_f32 v[20:21], v[10:11], v[188:189] op_sel_hi:[1,0]
	v_cvt_pk_fp8_f32 v22, v18, v19 op_sel:[0,0,1]
	v_mov_b64_e32 v[18:19], s[74:75]
	v_cvt_pk_fp8_f32 v26, v24, v25
	v_cvt_pk_fp8_f32 v23, v20, v21 op_sel:[0,0,1]
	v_mad_i64_i32 v[18:19], s[8:9], v17, s38, v[18:19]
	v_pk_mul_f32 v[24:25], v[0:1], v[188:189] op_sel_hi:[1,0]
	v_mov_b32_e32 v27, 0
	v_lshl_add_u64 v[18:19], v[18:19], 0, s[28:29]
	v_cvt_pk_fp8_f32 v27, v24, v25
	v_lshl_add_u64 v[18:19], v[18:19], 0, s[14:15]
	v_pk_mul_f32 v[20:21], v[6:7], v[188:189] op_sel_hi:[1,0]
	v_lshl_add_u64 v[18:19], v[18:19], 0, v[136:137]
	v_cvt_pk_fp8_f32 v26, v20, v21 op_sel:[0,0,1]
	global_store_dwordx2 v[18:19], v[22:23], off
	v_pk_mul_f32 v[18:19], v[2:3], v[188:189] op_sel_hi:[1,0]
	s_add_u32 s8, s76, s57
	v_cvt_pk_fp8_f32 v27, v18, v19 op_sel:[0,0,1]
	v_lshrrev_b32_e32 v18, 8, v26
	ds_write_b8 v164, v26
	ds_write_b8 v164, v18 offset:64
	ds_write_b8_d16_hi v164, v26 offset:128
	v_lshrrev_b32_e32 v18, 24, v26
	ds_write_b8 v164, v18 offset:192
	ds_write_b8 v164, v27 offset:256
	v_lshrrev_b32_e32 v18, 8, v27
	s_addc_u32 s9, s77, 0
	ds_write_b8 v164, v18 offset:320
	ds_write_b8_d16_hi v164, v27 offset:384
	v_lshrrev_b32_e32 v18, 24, v27
	s_add_u32 s8, s8, s34
	ds_write_b8 v164, v18 offset:448
	s_addc_u32 s9, s9, s35
	s_waitcnt lgkmcnt(0)
	s_add_u32 s8, s8, s10
	s_addc_u32 s9, s9, 0
	ds_read_b128 v[18:21], v165
	ds_read_b128 v[22:25], v166
	s_add_u32 s8, s8, s44
	s_addc_u32 s9, s9, s48
	s_add_u32 s8, s8, 0x4000
	s_addc_u32 s9, s9, 0
	v_lshl_add_u64 v[26:27], s[8:9], 0, v[138:139]
	v_lshl_add_u64 v[28:29], v[26:27], 0, v[82:83]
	s_waitcnt lgkmcnt(1)
	global_store_dwordx4 v[28:29], v[18:21], off
	s_nop 1
	v_lshl_add_u64 v[18:19], v[26:27], 0, v[80:81]
	s_waitcnt lgkmcnt(0)
	global_store_dwordx4 v[18:19], v[22:25], off
	s_waitcnt lgkmcnt(0)
	s_cbranch_execz .LBB0_394

; #define EPI_LOOP_ROWS  _Pragma("unroll") for (int ai = 0; ai < 2; ++ai) _Pragma("unroll") for (int m = 0; m < 4; ++m)
; __device__ __forceinline__ u32x4 pack8(f32x4 v0, f32x4 v1) { u32x4 w; w.x = cvt_pk_bf16(v0[0], v0[1]); w.y = cvt_pk_bf16(v0[2], v0[3]); w.z = cvt_pk_bf16(v1[0], v1[1]); w.w = cvt_pk_bf16(v1[2], v1[3]); return w; }
;     __device__ __forceinline__ void operator()(const Acc& acc, const Unit& u, int wr, int wc, int fr, int fq) const {
;     ...
;         EPI_LOOP_ROWS { const int row = u.pm * 256 + ai * HALF + wr * 64 + m * 16 + fr; const float s = rstd[row * 2 + which]; bf16_t* rowp = base + (size_t)row * ld + col0;
;             if (which == 0) {
; #pragma unroll
;                 for (int bj = 0; bj < 2; ++bj) *(u32x4*)(rowp + bj * HALF) = pack8(acc[ai][bj][m][0] * s, acc[ai][bj][m][1] * s);
.LBB0_394:
	v_mad_i64_i32 v[18:19], s[8:9], s30, v17, 0
	v_lshl_add_u64 v[18:19], v[18:19], 1, v[152:153]
	v_pk_mul_f32 v[14:15], v[14:15], v[188:189] op_sel_hi:[1,0]
	v_pk_mul_f32 v[12:13], v[12:13], v[188:189] op_sel_hi:[1,0]
	v_pk_mul_f32 v[20:21], v[10:11], v[188:189] op_sel_hi:[1,0]
	v_pk_mul_f32 v[10:11], v[8:9], v[188:189] op_sel_hi:[1,0]
	v_cvt_pk_bf16_f32 v8, v12, v13
	v_cvt_pk_bf16_f32 v9, v14, v15
	v_pk_mul_f32 v[6:7], v[6:7], v[188:189] op_sel_hi:[1,0]
	v_cvt_pk_bf16_f32 v10, v10, v11
	v_cvt_pk_bf16_f32 v11, v20, v21
	global_store_dwordx4 v[18:19], v[8:11], off
	v_pk_mul_f32 v[4:5], v[4:5], v[188:189] op_sel_hi:[1,0]
	s_nop 0
	v_pk_mul_f32 v[8:9], v[2:3], v[188:189] op_sel_hi:[1,0]
	v_pk_mul_f32 v[2:3], v[0:1], v[188:189] op_sel_hi:[1,0]
	v_cvt_pk_bf16_f32 v0, v4, v5
	v_cvt_pk_bf16_f32 v1, v6, v7
	s_nop 0
	v_cvt_pk_bf16_f32 v2, v2, v3
	v_cvt_pk_bf16_f32 v3, v8, v9
	global_store_dwordx4 v[18:19], v[0:3], off offset:256
	s_and_b64 vcc, exec, s[6:7]
	s_mov_b64 s[6:7], -1
	s_cbranch_vccnz .LBB0_350
